# grid barriers: acquire invalidate issued at arrival (before the poll) instead of after the release is observed
# speedup vs baseline: 1.0286x; 1.0038x over previous
.LBB0_152:
	s_or_b64 exec, exec, s[10:11]
	v_cvt_f32_u32_e32 v4, v2
	s_waitcnt vmcnt(0)
	v_readfirstlane_b32 s8, v3
	v_sub_u32_e32 v3, 0, v2
	v_rcp_iflag_f32_e32 v4, v4
	v_add_u32_e32 v5, s8, v1
	v_mul_f32_e32 v4, 0x4f7ffffe, v4
	v_cvt_u32_f32_e32 v4, v4
	v_mul_lo_u32 v1, v3, v4
	v_mul_hi_u32 v1, v4, v1
	v_add_u32_e32 v1, v4, v1
	v_mul_hi_u32 v1, v5, v1
	v_mul_lo_u32 v3, v1, v2
	v_sub_u32_e32 v3, v5, v3
	v_add_u32_e32 v4, 1, v1
	v_cmp_ge_u32_e32 vcc, v3, v2
	s_nop 1
	v_cndmask_b32_e32 v1, v1, v4, vcc
	v_sub_u32_e32 v4, v3, v2
	v_cndmask_b32_e32 v3, v3, v4, vcc
	v_add_u32_e32 v4, 1, v1
	v_cmp_ge_u32_e32 vcc, v3, v2
	v_add_u32_e32 v3, 1, v5
	s_nop 0
	v_cndmask_b32_e32 v1, v1, v4, vcc
	v_mul_lo_u32 v4, v2, v1
	v_add_u32_e32 v2, v4, v2
	v_cmp_ne_u32_e32 vcc, v3, v2
	s_and_saveexec_b64 s[8:9], vcc
	s_xor_b64 s[8:9], exec, s[8:9]
	s_cbranch_execz .LBB0_166
	s_waitcnt lgkmcnt(0)
	buffer_inv sc1
	v_mov_b32_e32 v0, 0x2000
	global_load_dword v0, v0, s[6:7] offset:1024 sc1
	s_add_u32 s22, s6, 0x2400
	s_addc_u32 s23, s7, 0
	s_waitcnt vmcnt(0)
	v_cmp_eq_u32_e32 vcc, v0, v1
	s_and_saveexec_b64 s[10:11], vcc
	s_cbranch_execz .LBB0_165
	s_add_u32 s20, s40, 0x4200
	s_addc_u32 s21, s41, 0
	s_mov_b32 s26, 1
	s_mov_b64 s[24:25], 0
	v_mov_b32_e32 v0, 0
	s_branch .LBB0_156

.LBB0_165:
	s_or_b64 exec, exec, s[10:11]
	s_waitcnt vmcnt(0)
	s_waitcnt vmcnt(0)
.LBB0_166:
	s_andn2_saveexec_b64 s[8:9], s[8:9]
	s_cbranch_execz .LBB0_186
	s_mov_b64 s[8:9], exec
	buffer_wbl2 sc1
	s_waitcnt lgkmcnt(0)
	s_waitcnt vmcnt(0)
	buffer_inv sc1
	v_mbcnt_lo_u32_b32 v1, s8, 0
	v_mbcnt_hi_u32_b32 v1, s9, v1
	v_cmp_eq_u32_e32 vcc, 0, v1
	s_and_saveexec_b64 s[10:11], vcc
	s_cbranch_execz .LBB0_169
	s_bcnt1_i32_b64 s8, s[8:9]
	v_mov_b32_e32 v2, 0x7000
	v_mov_b32_e32 v3, s8
	global_atomic_add v2, v2, v3, s[40:41] offset:1024 sc0

.LBB0_183:
	s_or_b64 exec, exec, s[8:9]
	s_mov_b64 s[8:9], exec
	v_mbcnt_lo_u32_b32 v0, s8, 0
	v_mbcnt_hi_u32_b32 v0, s9, v0
	v_cmp_eq_u32_e32 vcc, 0, v0
	s_waitcnt vmcnt(0)
	s_and_saveexec_b64 s[10:11], vcc
	s_cbranch_execz .LBB0_185
	s_bcnt1_i32_b64 s8, s[8:9]
	v_mov_b32_e32 v0, 0x2000
	v_mov_b32_e32 v1, s8
	global_atomic_add v0, v1, s[6:7] offset:1024

.LBB0_361:
	s_or_b64 exec, exec, s[10:11]
	v_cvt_f32_u32_e32 v4, v2
	s_waitcnt vmcnt(0)
	v_readfirstlane_b32 s8, v3
	v_sub_u32_e32 v3, 0, v2
	v_rcp_iflag_f32_e32 v4, v4
	v_add_u32_e32 v5, s8, v1
	v_mul_f32_e32 v4, 0x4f7ffffe, v4
	v_cvt_u32_f32_e32 v4, v4
	v_mul_lo_u32 v1, v3, v4
	v_mul_hi_u32 v1, v4, v1
	v_add_u32_e32 v1, v4, v1
	v_mul_hi_u32 v1, v5, v1
	v_mul_lo_u32 v3, v1, v2
	v_sub_u32_e32 v3, v5, v3
	v_add_u32_e32 v4, 1, v1
	v_cmp_ge_u32_e32 vcc, v3, v2
	s_nop 1
	v_cndmask_b32_e32 v1, v1, v4, vcc
	v_sub_u32_e32 v4, v3, v2
	v_cndmask_b32_e32 v3, v3, v4, vcc
	v_add_u32_e32 v4, 1, v1
	v_cmp_ge_u32_e32 vcc, v3, v2
	v_add_u32_e32 v3, 1, v5
	s_nop 0
	v_cndmask_b32_e32 v1, v1, v4, vcc
	v_mul_lo_u32 v4, v2, v1
	v_add_u32_e32 v2, v4, v2
	v_cmp_ne_u32_e32 vcc, v3, v2
	s_and_saveexec_b64 s[8:9], vcc
	s_xor_b64 s[8:9], exec, s[8:9]
	s_cbranch_execz .LBB0_375
	s_waitcnt lgkmcnt(0)
	buffer_inv sc1
	v_mov_b32_e32 v0, 0x2000
	global_load_dword v0, v0, s[6:7] offset:1024 sc1
	s_add_u32 s16, s6, 0x2400
	s_addc_u32 s17, s7, 0
	s_waitcnt vmcnt(0)
	v_cmp_eq_u32_e32 vcc, v0, v1
	s_and_saveexec_b64 s[10:11], vcc
	s_cbranch_execz .LBB0_374
	s_add_u32 s14, s40, 0x4200
	s_addc_u32 s15, s41, 0
	s_mov_b32 s26, 1
	s_mov_b64 s[18:19], 0
	v_mov_b32_e32 v0, 0
	s_branch .LBB0_365

.LBB0_639:
	s_or_b64 exec, exec, s[10:11]
	v_cvt_f32_u32_e32 v4, v2
	s_waitcnt vmcnt(0)
	v_readfirstlane_b32 s8, v3
	v_sub_u32_e32 v3, 0, v2
	v_rcp_iflag_f32_e32 v4, v4
	v_add_u32_e32 v5, s8, v1
	v_mul_f32_e32 v4, 0x4f7ffffe, v4
	v_cvt_u32_f32_e32 v4, v4
	v_mul_lo_u32 v1, v3, v4
	v_mul_hi_u32 v1, v4, v1
	v_add_u32_e32 v1, v4, v1
	v_mul_hi_u32 v1, v5, v1
	v_mul_lo_u32 v3, v1, v2
	v_sub_u32_e32 v3, v5, v3
	v_add_u32_e32 v4, 1, v1
	v_cmp_ge_u32_e32 vcc, v3, v2
	s_nop 1
	v_cndmask_b32_e32 v1, v1, v4, vcc
	v_sub_u32_e32 v4, v3, v2
	v_cndmask_b32_e32 v3, v3, v4, vcc
	v_add_u32_e32 v4, 1, v1
	v_cmp_ge_u32_e32 vcc, v3, v2
	v_add_u32_e32 v3, 1, v5
	s_nop 0
	v_cndmask_b32_e32 v1, v1, v4, vcc
	v_mul_lo_u32 v4, v2, v1
	v_add_u32_e32 v2, v4, v2
	v_cmp_ne_u32_e32 vcc, v3, v2
	s_and_saveexec_b64 s[8:9], vcc
	s_xor_b64 s[8:9], exec, s[8:9]
	s_cbranch_execz .LBB0_653
	s_waitcnt lgkmcnt(0)
	buffer_inv sc1
	v_mov_b32_e32 v0, 0x2000
	global_load_dword v0, v0, s[6:7] offset:1024 sc1
	s_add_u32 s16, s6, 0x2400
	s_addc_u32 s17, s7, 0
	s_waitcnt vmcnt(0)
	v_cmp_eq_u32_e32 vcc, v0, v1
	s_and_saveexec_b64 s[10:11], vcc
	s_cbranch_execz .LBB0_652
	s_add_u32 s12, s40, 0x4200
	s_addc_u32 s13, s41, 0
	s_mov_b32 s26, 1
	s_mov_b64 s[18:19], 0
	v_mov_b32_e32 v0, 0
	s_branch .LBB0_643

.LBB0_747:
	s_or_b64 exec, exec, s[10:11]
	v_cvt_f32_u32_e32 v4, v2
	s_waitcnt vmcnt(0)
	v_readfirstlane_b32 s8, v3
	v_sub_u32_e32 v3, 0, v2
	v_rcp_iflag_f32_e32 v4, v4
	v_add_u32_e32 v5, s8, v1
	v_mul_f32_e32 v4, 0x4f7ffffe, v4
	v_cvt_u32_f32_e32 v4, v4
	v_mul_lo_u32 v1, v3, v4
	v_mul_hi_u32 v1, v4, v1
	v_add_u32_e32 v1, v4, v1
	v_mul_hi_u32 v1, v5, v1
	v_mul_lo_u32 v3, v1, v2
	v_sub_u32_e32 v3, v5, v3
	v_add_u32_e32 v4, 1, v1
	v_cmp_ge_u32_e32 vcc, v3, v2
	s_nop 1
	v_cndmask_b32_e32 v1, v1, v4, vcc
	v_sub_u32_e32 v4, v3, v2
	v_cndmask_b32_e32 v3, v3, v4, vcc
	v_add_u32_e32 v4, 1, v1
	v_cmp_ge_u32_e32 vcc, v3, v2
	v_add_u32_e32 v3, 1, v5
	s_nop 0
	v_cndmask_b32_e32 v1, v1, v4, vcc
	v_mul_lo_u32 v4, v2, v1
	v_add_u32_e32 v2, v4, v2
	v_cmp_ne_u32_e32 vcc, v3, v2
	s_and_saveexec_b64 s[8:9], vcc
	s_xor_b64 s[8:9], exec, s[8:9]
	s_cbranch_execz .LBB0_761
	s_waitcnt lgkmcnt(0)
	buffer_inv sc1
	v_mov_b32_e32 v0, 0x2000
	global_load_dword v0, v0, s[6:7] offset:1024 sc1
	s_add_u32 s14, s6, 0x2400
	s_addc_u32 s15, s7, 0
	s_waitcnt vmcnt(0)
	v_cmp_eq_u32_e32 vcc, v0, v1
	s_and_saveexec_b64 s[10:11], vcc
	s_cbranch_execz .LBB0_760
	s_add_u32 s12, s40, 0x4200
	s_addc_u32 s13, s41, 0
	s_mov_b32 s26, 1
	s_mov_b64 s[16:17], 0
	v_mov_b32_e32 v0, 0
	s_branch .LBB0_751

.LBB0_886:
	s_or_b64 exec, exec, s[12:13]
	v_cvt_f32_u32_e32 v38, v36
	s_waitcnt vmcnt(0)
	v_readfirstlane_b32 s10, v37
	v_sub_u32_e32 v37, 0, v36
	v_rcp_iflag_f32_e32 v38, v38
	v_add_u32_e32 v39, s10, v33
	v_mul_f32_e32 v38, 0x4f7ffffe, v38
	v_cvt_u32_f32_e32 v38, v38
	v_mul_lo_u32 v33, v37, v38
	v_mul_hi_u32 v33, v38, v33
	v_add_u32_e32 v33, v38, v33
	v_mul_hi_u32 v33, v39, v33
	v_mul_lo_u32 v37, v33, v36
	v_sub_u32_e32 v37, v39, v37
	v_add_u32_e32 v38, 1, v33
	v_cmp_ge_u32_e32 vcc, v37, v36
	s_nop 1
	v_cndmask_b32_e32 v33, v33, v38, vcc
	v_sub_u32_e32 v38, v37, v36
	v_cndmask_b32_e32 v37, v37, v38, vcc
	v_add_u32_e32 v38, 1, v33
	v_cmp_ge_u32_e32 vcc, v37, v36
	v_add_u32_e32 v37, 1, v39
	s_nop 0
	v_cndmask_b32_e32 v33, v33, v38, vcc
	v_mul_lo_u32 v38, v36, v33
	v_add_u32_e32 v36, v38, v36
	v_cmp_ne_u32_e32 vcc, v37, v36
	s_and_saveexec_b64 s[10:11], vcc
	s_xor_b64 s[10:11], exec, s[10:11]
	s_cbranch_execz .LBB0_900
	s_waitcnt lgkmcnt(0)
	buffer_inv sc1
	v_mov_b32_e32 v32, 0x2000
	global_load_dword v32, v32, s[8:9] offset:1024 sc1
	s_add_u32 s16, s8, 0x2400
	s_addc_u32 s17, s9, 0
	s_waitcnt vmcnt(0)
	v_cmp_eq_u32_e32 vcc, v32, v33
	s_and_saveexec_b64 s[12:13], vcc
	s_cbranch_execz .LBB0_899
	s_add_u32 s14, s40, 0x4200
	s_addc_u32 s15, s41, 0
	s_mov_b32 s28, 1
	s_mov_b64 s[18:19], 0
	v_mov_b32_e32 v32, 0
	s_branch .LBB0_890

.LBB0_899:
	s_or_b64 exec, exec, s[12:13]
	s_waitcnt vmcnt(0)
	s_waitcnt vmcnt(0)
.LBB0_900:
	s_andn2_saveexec_b64 s[10:11], s[10:11]
	s_cbranch_execz .LBB0_920
	s_mov_b64 s[10:11], exec
	buffer_wbl2 sc1
	s_waitcnt lgkmcnt(0)
	s_waitcnt vmcnt(0)
	buffer_inv sc1
	v_mbcnt_lo_u32_b32 v33, s10, 0
	v_mbcnt_hi_u32_b32 v33, s11, v33
	v_cmp_eq_u32_e32 vcc, 0, v33
	s_and_saveexec_b64 s[12:13], vcc
	s_cbranch_execz .LBB0_903
	s_bcnt1_i32_b64 s10, s[10:11]
	v_mov_b32_e32 v36, 0x7000
	v_mov_b32_e32 v37, s10
	global_atomic_add v36, v36, v37, s[40:41] offset:1024 sc0

.LBB0_917:
	s_or_b64 exec, exec, s[10:11]
	s_mov_b64 s[10:11], exec
	v_mbcnt_lo_u32_b32 v32, s10, 0
	v_mbcnt_hi_u32_b32 v32, s11, v32
	v_cmp_eq_u32_e32 vcc, 0, v32
	s_waitcnt vmcnt(0)
	s_and_saveexec_b64 s[12:13], vcc
	s_cbranch_execz .LBB0_919
	s_bcnt1_i32_b64 s10, s[10:11]
	v_mov_b32_e32 v32, 0x2000
	v_mov_b32_e32 v33, s10
	global_atomic_add v32, v33, s[8:9] offset:1024

.LBB0_972:
	s_or_b64 exec, exec, s[12:13]
	v_cvt_f32_u32_e32 v4, v2
	s_waitcnt vmcnt(0)
	v_readfirstlane_b32 s8, v3
	v_sub_u32_e32 v3, 0, v2
	v_rcp_iflag_f32_e32 v4, v4
	v_add_u32_e32 v5, s8, v1
	v_mul_f32_e32 v4, 0x4f7ffffe, v4
	v_cvt_u32_f32_e32 v4, v4
	v_mul_lo_u32 v1, v3, v4
	v_mul_hi_u32 v1, v4, v1
	v_add_u32_e32 v1, v4, v1
	v_mul_hi_u32 v1, v5, v1
	v_mul_lo_u32 v3, v1, v2
	v_sub_u32_e32 v3, v5, v3
	v_add_u32_e32 v4, 1, v1
	v_cmp_ge_u32_e32 vcc, v3, v2
	s_nop 1
	v_cndmask_b32_e32 v1, v1, v4, vcc
	v_sub_u32_e32 v4, v3, v2
	v_cndmask_b32_e32 v3, v3, v4, vcc
	v_add_u32_e32 v4, 1, v1
	v_cmp_ge_u32_e32 vcc, v3, v2
	v_add_u32_e32 v3, 1, v5
	s_nop 0
	v_cndmask_b32_e32 v1, v1, v4, vcc
	v_mul_lo_u32 v4, v2, v1
	v_add_u32_e32 v2, v4, v2
	v_cmp_ne_u32_e32 vcc, v3, v2
	s_and_saveexec_b64 s[8:9], vcc
	s_xor_b64 s[8:9], exec, s[8:9]
	s_cbranch_execz .LBB0_986
	s_waitcnt lgkmcnt(0)
	buffer_inv sc1
	v_mov_b32_e32 v0, 0x2000
	global_load_dword v0, v0, s[6:7] offset:1024 sc1
	s_add_u32 s16, s6, 0x2400
	s_addc_u32 s17, s7, 0
	s_waitcnt vmcnt(0)
	v_cmp_eq_u32_e32 vcc, v0, v1
	s_and_saveexec_b64 s[12:13], vcc
	s_cbranch_execz .LBB0_985
	s_add_u32 s14, s40, 0x4200
	s_addc_u32 s15, s41, 0
	s_mov_b32 s28, 1
	s_mov_b64 s[18:19], 0
	v_mov_b32_e32 v0, 0
	s_branch .LBB0_976

.LBB0_986:
	s_andn2_saveexec_b64 s[8:9], s[8:9]
	s_cbranch_execz .LBB0_1006
	s_mov_b64 s[8:9], exec
	buffer_wbl2 sc1
	s_waitcnt lgkmcnt(0)
	s_waitcnt vmcnt(0)
	buffer_inv sc1
	v_mbcnt_lo_u32_b32 v1, s8, 0
	v_mbcnt_hi_u32_b32 v1, s9, v1
	v_cmp_eq_u32_e32 vcc, 0, v1
	s_and_saveexec_b64 s[12:13], vcc
	s_cbranch_execz .LBB0_989
	s_bcnt1_i32_b64 s8, s[8:9]
	v_mov_b32_e32 v2, 0x7000
	v_mov_b32_e32 v3, s8
	global_atomic_add v2, v2, v3, s[40:41] offset:1024 sc0

.LBB0_1003:
	s_or_b64 exec, exec, s[8:9]
	s_mov_b64 s[8:9], exec
	v_mbcnt_lo_u32_b32 v0, s8, 0
	v_mbcnt_hi_u32_b32 v0, s9, v0
	v_cmp_eq_u32_e32 vcc, 0, v0
	s_waitcnt vmcnt(0)
	s_and_saveexec_b64 s[12:13], vcc
	s_cbranch_execz .LBB0_1005
	s_bcnt1_i32_b64 s8, s[8:9]
	v_mov_b32_e32 v0, 0x2000
	v_mov_b32_e32 v1, s8
	global_atomic_add v0, v1, s[6:7] offset:1024

.LBB0_1078:
	s_or_b64 exec, exec, s[14:15]
	v_cvt_f32_u32_e32 v4, v2
	s_waitcnt vmcnt(0)
	v_readfirstlane_b32 s12, v3
	v_sub_u32_e32 v3, 0, v2
	v_rcp_iflag_f32_e32 v4, v4
	v_add_u32_e32 v5, s12, v1
	v_mul_f32_e32 v4, 0x4f7ffffe, v4
	v_cvt_u32_f32_e32 v4, v4
	v_mul_lo_u32 v1, v3, v4
	v_mul_hi_u32 v1, v4, v1
	v_add_u32_e32 v1, v4, v1
	v_mul_hi_u32 v1, v5, v1
	v_mul_lo_u32 v3, v1, v2
	v_sub_u32_e32 v3, v5, v3
	v_add_u32_e32 v4, 1, v1
	v_cmp_ge_u32_e32 vcc, v3, v2
	s_nop 1
	v_cndmask_b32_e32 v1, v1, v4, vcc
	v_sub_u32_e32 v4, v3, v2
	v_cndmask_b32_e32 v3, v3, v4, vcc
	v_add_u32_e32 v4, 1, v1
	v_cmp_ge_u32_e32 vcc, v3, v2
	v_add_u32_e32 v3, 1, v5
	s_nop 0
	v_cndmask_b32_e32 v1, v1, v4, vcc
	v_mul_lo_u32 v4, v2, v1
	v_add_u32_e32 v2, v4, v2
	v_cmp_ne_u32_e32 vcc, v3, v2
	s_and_saveexec_b64 s[12:13], vcc
	s_xor_b64 s[12:13], exec, s[12:13]
	s_cbranch_execz .LBB0_1092
	s_waitcnt lgkmcnt(0)
	buffer_inv sc1
	v_mov_b32_e32 v0, 0x2000
	global_load_dword v0, v0, s[10:11] offset:1024 sc1
	s_add_u32 s20, s10, 0x2400
	s_addc_u32 s21, s11, 0
	s_waitcnt vmcnt(0)
	v_cmp_eq_u32_e32 vcc, v0, v1
	s_and_saveexec_b64 s[14:15], vcc
	s_cbranch_execz .LBB0_1091
	s_add_u32 s16, s40, 0x4200
	s_addc_u32 s17, s41, 0
	s_mov_b32 s34, 1
	s_mov_b64 s[22:23], 0
	v_mov_b32_e32 v0, 0
	s_branch .LBB0_1082

.LBB0_1091:
	s_or_b64 exec, exec, s[14:15]
	s_waitcnt vmcnt(0)
	s_waitcnt vmcnt(0)
.LBB0_1092:
	s_andn2_saveexec_b64 s[12:13], s[12:13]
	s_cbranch_execz .LBB0_1112
	s_mov_b64 s[12:13], exec
	buffer_wbl2 sc1
	s_waitcnt lgkmcnt(0)
	s_waitcnt vmcnt(0)
	buffer_inv sc1
	v_mbcnt_lo_u32_b32 v1, s12, 0
	v_mbcnt_hi_u32_b32 v1, s13, v1
	v_cmp_eq_u32_e32 vcc, 0, v1
	s_and_saveexec_b64 s[14:15], vcc
	s_cbranch_execz .LBB0_1095
	s_bcnt1_i32_b64 s12, s[12:13]
	v_mov_b32_e32 v2, 0x7000
	v_mov_b32_e32 v3, s12
	global_atomic_add v2, v2, v3, s[40:41] offset:1024 sc0

.LBB0_1109:
	s_or_b64 exec, exec, s[12:13]
	s_mov_b64 s[12:13], exec
	v_mbcnt_lo_u32_b32 v0, s12, 0
	v_mbcnt_hi_u32_b32 v0, s13, v0
	v_cmp_eq_u32_e32 vcc, 0, v0
	s_waitcnt vmcnt(0)
	s_and_saveexec_b64 s[14:15], vcc
	s_cbranch_execz .LBB0_1111
	s_bcnt1_i32_b64 s12, s[12:13]
	v_mov_b32_e32 v0, 0x2000
	v_mov_b32_e32 v1, s12
	global_atomic_add v0, v1, s[10:11] offset:1024

.LBB0_1196:
	s_or_b64 exec, exec, s[10:11]
	v_cvt_f32_u32_e32 v4, v2
	s_waitcnt vmcnt(0)
	v_readfirstlane_b32 s8, v3
	v_sub_u32_e32 v3, 0, v2
	v_rcp_iflag_f32_e32 v4, v4
	v_add_u32_e32 v5, s8, v1
	v_mul_f32_e32 v4, 0x4f7ffffe, v4
	v_cvt_u32_f32_e32 v4, v4
	v_mul_lo_u32 v1, v3, v4
	v_mul_hi_u32 v1, v4, v1
	v_add_u32_e32 v1, v4, v1
	v_mul_hi_u32 v1, v5, v1
	v_mul_lo_u32 v3, v1, v2
	v_sub_u32_e32 v3, v5, v3
	v_add_u32_e32 v4, 1, v1
	v_cmp_ge_u32_e32 vcc, v3, v2
	s_nop 1
	v_cndmask_b32_e32 v1, v1, v4, vcc
	v_sub_u32_e32 v4, v3, v2
	v_cndmask_b32_e32 v3, v3, v4, vcc
	v_add_u32_e32 v4, 1, v1
	v_cmp_ge_u32_e32 vcc, v3, v2
	v_add_u32_e32 v3, 1, v5
	s_nop 0
	v_cndmask_b32_e32 v1, v1, v4, vcc
	v_mul_lo_u32 v4, v2, v1
	v_add_u32_e32 v2, v4, v2
	v_cmp_ne_u32_e32 vcc, v3, v2
	s_and_saveexec_b64 s[8:9], vcc
	s_xor_b64 s[8:9], exec, s[8:9]
	s_cbranch_execz .LBB0_1210
	s_waitcnt lgkmcnt(0)
	buffer_inv sc1
	v_mov_b32_e32 v0, 0x2000
	global_load_dword v0, v0, s[6:7] offset:1024 sc1
	s_add_u32 s16, s6, 0x2400
	s_addc_u32 s17, s7, 0
	s_waitcnt vmcnt(0)
	v_cmp_eq_u32_e32 vcc, v0, v1
	s_and_saveexec_b64 s[10:11], vcc
	s_cbranch_execz .LBB0_1209
	s_add_u32 s14, s40, 0x4200
	s_addc_u32 s15, s41, 0
	s_mov_b32 s30, 1
	s_mov_b64 s[20:21], 0
	v_mov_b32_e32 v0, 0
	s_branch .LBB0_1200

.LBB0_1305:
	s_or_b64 exec, exec, s[10:11]
	v_cvt_f32_u32_e32 v4, v2
	s_waitcnt vmcnt(0)
	v_readfirstlane_b32 s3, v3
	v_sub_u32_e32 v3, 0, v2
	v_rcp_iflag_f32_e32 v4, v4
	v_add_u32_e32 v5, s3, v1
	v_mul_f32_e32 v4, 0x4f7ffffe, v4
	v_cvt_u32_f32_e32 v4, v4
	v_mul_lo_u32 v1, v3, v4
	v_mul_hi_u32 v1, v4, v1
	v_add_u32_e32 v1, v4, v1
	v_mul_hi_u32 v1, v5, v1
	v_mul_lo_u32 v3, v1, v2
	v_sub_u32_e32 v3, v5, v3
	v_add_u32_e32 v4, 1, v1
	v_cmp_ge_u32_e32 vcc, v3, v2
	s_nop 1
	v_cndmask_b32_e32 v1, v1, v4, vcc
	v_sub_u32_e32 v4, v3, v2
	v_cndmask_b32_e32 v3, v3, v4, vcc
	v_add_u32_e32 v4, 1, v1
	v_cmp_ge_u32_e32 vcc, v3, v2
	v_add_u32_e32 v3, 1, v5
	s_nop 0
	v_cndmask_b32_e32 v1, v1, v4, vcc
	v_mul_lo_u32 v4, v2, v1
	v_add_u32_e32 v2, v4, v2
	v_cmp_ne_u32_e32 vcc, v3, v2
	s_and_saveexec_b64 s[8:9], vcc
	s_xor_b64 s[8:9], exec, s[8:9]
	s_cbranch_execz .LBB0_1319
	s_waitcnt lgkmcnt(0)
	buffer_inv sc1
	v_mov_b32_e32 v0, 0x2000
	global_load_dword v0, v0, s[6:7] offset:1024 sc1
	s_add_u32 s14, s6, 0x2400
	s_addc_u32 s15, s7, 0
	s_waitcnt vmcnt(0)
	v_cmp_eq_u32_e32 vcc, v0, v1
	s_and_saveexec_b64 s[10:11], vcc
	s_cbranch_execz .LBB0_1318
	s_add_u32 s12, s40, 0x4200
	s_addc_u32 s13, s41, 0
	s_mov_b32 s3, 1
	s_mov_b64 s[16:17], 0
	v_mov_b32_e32 v0, 0
	s_branch .LBB0_1309

.LBB0_1319:
	s_andn2_saveexec_b64 s[8:9], s[8:9]
	s_cbranch_execz .LBB0_1339
	s_mov_b64 s[8:9], exec
	buffer_wbl2 sc1
	s_waitcnt lgkmcnt(0)
	s_waitcnt vmcnt(0)
	buffer_inv sc1
	v_mbcnt_lo_u32_b32 v1, s8, 0
	v_mbcnt_hi_u32_b32 v1, s9, v1
	v_cmp_eq_u32_e32 vcc, 0, v1
	s_and_saveexec_b64 s[10:11], vcc
	s_cbranch_execz .LBB0_1322
	s_bcnt1_i32_b64 s3, s[8:9]
	v_mov_b32_e32 v2, 0x7000
	v_mov_b32_e32 v3, s3
	global_atomic_add v2, v2, v3, s[40:41] offset:1024 sc0

.LBB0_1336:
	s_or_b64 exec, exec, s[8:9]
	s_mov_b64 s[8:9], exec
	v_mbcnt_lo_u32_b32 v0, s8, 0
	v_mbcnt_hi_u32_b32 v0, s9, v0
	v_cmp_eq_u32_e32 vcc, 0, v0
	s_waitcnt vmcnt(0)
	s_and_saveexec_b64 s[10:11], vcc
	s_cbranch_execz .LBB0_1338
	s_bcnt1_i32_b64 s3, s[8:9]
	v_mov_b32_e32 v0, 0x2000
	v_mov_b32_e32 v1, s3
	global_atomic_add v0, v1, s[6:7] offset:1024
